# P1 cumsum workgroups: gain-table fill loads issued before the cumsum
# baseline (speedup 1.0000x reference)
.Lwb_chk_done:
.LBB0_168:
	s_cmp_lt_i32 s3, 2
	s_cselect_b64 s[8:9], -1, 0
	s_and_b64 s[36:37], s[8:9], s[6:7]
	s_andn2_b64 vcc, exec, s[36:37]
	s_cbranch_vccnz .LBB0_226
	s_mov_b64 s[6:7], s[0:1]
	s_mov_b32 s101, 0
	s_cmp_gt_i32 s2, 63
	s_cbranch_scc1 .LBB0_182
	s_mov_b32 s101, 1
	s_cmp_gt_u32 s96, 1
	s_cbranch_scc1 .Lgl_pf_done
	s_cmp_eq_u32 s96, 0
	s_cbranch_scc0 .Lgl_pf_w1
	s_load_dwordx2 s[98:99], s[0:1], 0x28
	s_branch .Lgl_pf_ld
.Lgl_pf_w1:
	s_load_dwordx2 s[98:99], s[0:1], 0x30
.Lgl_pf_ld:
	v_lshlrev_b32_e32 v30, 2, v210
	s_waitcnt lgkmcnt(0)
	global_load_dword v31, v30, s[98:99]
.Lgl_pf_done:
	s_load_dwordx2 s[6:7], s[6:7], 0xa8
	v_lshlrev_b32_e32 v0, 5, v208
	s_waitcnt lgkmcnt(0)
	v_mov_b32_e32 v1, 0
	s_mov_b64 s[8:9], 0x100000
	v_mbcnt_lo_u32_b32 v2, -1, 0
	v_lshl_add_u64 v[0:1], s[6:7], 0, v[0:1]
	v_lshl_add_u64 v[4:5], v[0:1], 0, s[8:9]
	s_lshl_b32 s8, s96, 2
	v_mbcnt_hi_u32_b32 v2, -1, v2
	s_add_i32 s39, s8, 0
	s_mov_b64 s[8:9], 0x200000
	v_and_b32_e32 v3, 64, v2
	v_lshl_add_u64 v[6:7], v[0:1], 0, s[8:9]
	v_add_u32_e32 v0, -1, v2
	v_cmp_lt_i32_e32 vcc, v0, v3
	s_add_i32 s39, s39, 0x22000
	s_cmp_gt_u32 s79, 63
	v_cndmask_b32_e32 v0, v0, v2, vcc
	v_lshlrev_b32_e32 v13, 2, v0
	v_add_u32_e32 v0, -2, v2
	v_cmp_lt_i32_e32 vcc, v0, v3
	s_cselect_b64 s[20:21], -1, 0
	s_add_i32 s22, s96, -1
	v_cndmask_b32_e32 v0, v0, v2, vcc
	v_lshlrev_b32_e32 v14, 2, v0
	v_add_u32_e32 v0, -4, v2
	v_cmp_lt_i32_e32 vcc, v0, v3
	s_bfe_u32 s44, s79, 0x30006
	s_cmp_gt_u32 s22, 6
	v_cndmask_b32_e32 v0, v0, v2, vcc
	v_lshlrev_b32_e32 v15, 2, v0
	v_add_u32_e32 v0, -8, v2
	v_cmp_lt_i32_e32 vcc, v0, v3
	s_cselect_b64 s[22:23], -1, 0
	s_and_b32 s45, s96, 0x3fffff8
	v_cndmask_b32_e32 v0, v0, v2, vcc
	v_lshlrev_b32_e32 v16, 2, v0
	v_add_u32_e32 v0, -16, v2
	v_cmp_lt_i32_e32 vcc, v0, v3
	s_cmp_lg_u32 s44, 0
	s_cselect_b64 s[24:25], -1, 0
	v_cndmask_b32_e32 v0, v0, v2, vcc
	v_lshlrev_b32_e32 v17, 2, v0
	v_subrev_u32_e32 v0, 32, v2
	v_cmp_lt_i32_e32 vcc, v0, v3
	v_cmp_eq_u32_e64 s[6:7], 63, v210
	v_cmp_eq_u32_e64 s[8:9], 0, v210
	v_cndmask_b32_e32 v0, v0, v2, vcc
	v_lshlrev_b32_e32 v18, 2, v0
	v_cndmask_b32_e64 v0, 0, 1, s[20:21]
	v_cmp_ne_u32_e64 s[20:21], 1, v0
	v_cndmask_b32_e64 v0, 0, 1, s[22:23]
	v_cmp_ne_u32_e64 s[22:23], 1, v0
	v_cndmask_b32_e64 v0, 0, 1, s[24:25]
	v_cmp_gt_u32_e64 s[10:11], 2, v210
	v_cmp_gt_u32_e64 s[12:13], 4, v210
	v_cmp_gt_u32_e64 s[14:15], 8, v210
	v_cmp_gt_u32_e64 s[16:17], 16, v210
	v_cmp_gt_u32_e64 s[18:19], 32, v210
	s_add_i32 s46, 0, 0x22000
	v_cmp_ne_u32_e64 s[24:25], 1, v0
	s_mov_b32 s38, 0xbfb8aa3b
	s_mov_b32 s40, s2
	s_branch .LBB0_172

.LBB0_182:
	s_mov_b64 s[6:7], s[0:1]
	s_mov_b64 s[8:9], s[0:1]
	s_load_dwordx2 s[6:7], s[6:7], 0xa8
	s_load_dwordx2 s[10:11], s[8:9], 0xa8
	s_cmp_eq_u32 s101, 1
	s_cbranch_scc0 .Lgl_orig
	s_mov_b64 s[8:9], 0
	s_cmp_gt_u32 s96, 1
	s_cbranch_scc1 .Lgl_have
	s_waitcnt vmcnt(0)
	v_mov_b32_e32 v0, v31
	s_mov_b64 s[8:9], exec
	s_cmp_lg_u32 s96, 0
	s_cbranch_scc1 .Lgl_have
	v_mul_f32_e32 v0, 0x3e38aa3b, v31
	s_branch .Lgl_have
.Lgl_orig:
	v_cmp_lt_u32_e32 vcc, 63, v208
	s_mov_b64 s[8:9], 0
	s_and_saveexec_b64 s[12:13], vcc
	s_xor_b64 s[12:13], exec, s[12:13]
	s_cbranch_execnz .LBB0_221
	s_andn2_saveexec_b64 s[12:13], s[12:13]
	s_cbranch_execnz .LBB0_224

.Lgl_have:
	s_and_saveexec_b64 s[12:13], s[8:9]
	s_cbranch_execz .LBB0_186
